# RG-LRU conv stage (pass A and B): four row reads kept in flight in their own register quads, counted lgkmcnt waits per tap
# speedup vs baseline: 1.0102x; 1.0056x over previous
.LBB0_207:
	s_waitcnt lgkmcnt(0)
	ds_read_b128 v[138:141], v180 offset:11008
	ds_read_b128 v[222:225], v180 offset:11152
	ds_read_b128 v[226:229], v180 offset:11296
	ds_read_b128 v[230:233], v180 offset:11440
	s_add_i32 s43, s43, 16
	s_cmpk_lg_i32 s43, 0x80
	s_waitcnt lgkmcnt(3)
	v_lshlrev_b32_e32 v124, 16, v138
	v_and_b32_e32 v125, 0xffff0000, v138
	v_lshlrev_b32_e32 v120, 16, v139
	v_and_b32_e32 v121, 0xffff0000, v139
	v_lshlrev_b32_e32 v126, 16, v140
	v_and_b32_e32 v127, 0xffff0000, v140
	v_lshlrev_b32_e32 v122, 16, v141
	v_and_b32_e32 v123, 0xffff0000, v141
	ds_read_b128 v[138:141], v180 offset:12160
	v_pk_fma_f32 v[128:129], v[6:7], v[120:121], v[22:23]
	v_pk_fma_f32 v[130:131], v[2:3], v[122:123], v[18:19]
	v_pk_fma_f32 v[124:125], v[4:5], v[124:125], v[20:21]
	v_pk_fma_f32 v[126:127], v[0:1], v[126:127], v[16:17]
	s_waitcnt lgkmcnt(3)
	v_lshlrev_b32_e32 v132, 16, v222
	v_and_b32_e32 v133, 0xffff0000, v222
	v_lshlrev_b32_e32 v120, 16, v223
	v_and_b32_e32 v121, 0xffff0000, v223
	v_lshlrev_b32_e32 v134, 16, v224
	v_and_b32_e32 v135, 0xffff0000, v224
	v_lshlrev_b32_e32 v122, 16, v225
	v_and_b32_e32 v123, 0xffff0000, v225
	ds_read_b128 v[222:225], v180 offset:12304
	v_pk_fma_f32 v[128:129], v[14:15], v[120:121], v[128:129]
	v_pk_fma_f32 v[130:131], v[10:11], v[122:123], v[130:131]
	v_pk_fma_f32 v[124:125], v[12:13], v[132:133], v[124:125]
	v_pk_fma_f32 v[126:127], v[8:9], v[134:135], v[126:127]
	s_waitcnt lgkmcnt(3)
	v_lshlrev_b32_e32 v132, 16, v226
	v_and_b32_e32 v133, 0xffff0000, v226
	v_lshlrev_b32_e32 v120, 16, v227
	v_and_b32_e32 v121, 0xffff0000, v227
	v_lshlrev_b32_e32 v134, 16, v228
	v_and_b32_e32 v135, 0xffff0000, v228
	v_lshlrev_b32_e32 v122, 16, v229
	v_and_b32_e32 v123, 0xffff0000, v229
	ds_read_b128 v[226:229], v180 offset:12448
	v_pk_fma_f32 v[124:125], v[24:25], v[132:133], v[124:125]
	v_pk_fma_f32 v[128:129], v[26:27], v[120:121], v[128:129]
	v_pk_fma_f32 v[132:133], v[28:29], v[134:135], v[126:127]
	v_pk_fma_f32 v[126:127], v[30:31], v[122:123], v[130:131]
	s_waitcnt lgkmcnt(3)
	v_lshlrev_b32_e32 v130, 16, v230
	v_and_b32_e32 v131, 0xffff0000, v230
	v_lshlrev_b32_e32 v120, 16, v231
	v_and_b32_e32 v121, 0xffff0000, v231
	v_lshlrev_b32_e32 v134, 16, v232
	v_and_b32_e32 v135, 0xffff0000, v232
	v_lshlrev_b32_e32 v136, 16, v233
	v_and_b32_e32 v137, 0xffff0000, v233
	ds_read_b128 v[230:233], v180 offset:12592
	v_pk_fma_f32 v[122:123], v[34:35], v[120:121], v[128:129]
	v_pk_fma_f32 v[120:121], v[32:33], v[130:131], v[124:125]
	v_pk_fma_f32 v[126:127], v[38:39], v[136:137], v[126:127]
	v_pk_fma_f32 v[124:125], v[36:37], v[134:135], v[132:133]
	ds_write_b128 v179, v[120:123] offset:2304
	ds_write_b128 v179, v[124:127] offset:2320
	v_cvt_pk_bf16_f32 v120, v120, v121
	v_cvt_pk_bf16_f32 v121, v122, v123
	v_cvt_pk_bf16_f32 v122, v124, v125
	v_cvt_pk_bf16_f32 v123, v126, v127
	ds_write_b128 v180, v[120:123]
	s_waitcnt lgkmcnt(6)
	v_lshlrev_b32_e32 v124, 16, v138
	v_and_b32_e32 v125, 0xffff0000, v138
	v_lshlrev_b32_e32 v120, 16, v139
	v_and_b32_e32 v121, 0xffff0000, v139
	v_lshlrev_b32_e32 v126, 16, v140
	v_and_b32_e32 v127, 0xffff0000, v140
	v_lshlrev_b32_e32 v122, 16, v141
	v_and_b32_e32 v123, 0xffff0000, v141
	v_pk_fma_f32 v[128:129], v[6:7], v[120:121], v[22:23]
	v_pk_fma_f32 v[130:131], v[2:3], v[122:123], v[18:19]
	v_pk_fma_f32 v[124:125], v[4:5], v[124:125], v[20:21]
	v_pk_fma_f32 v[126:127], v[0:1], v[126:127], v[16:17]
	s_waitcnt lgkmcnt(5)
	v_lshlrev_b32_e32 v132, 16, v222
	v_and_b32_e32 v133, 0xffff0000, v222
	v_lshlrev_b32_e32 v120, 16, v223
	v_and_b32_e32 v121, 0xffff0000, v223
	v_lshlrev_b32_e32 v134, 16, v224
	v_and_b32_e32 v135, 0xffff0000, v224
	v_lshlrev_b32_e32 v122, 16, v225
	v_and_b32_e32 v123, 0xffff0000, v225
	v_pk_fma_f32 v[128:129], v[14:15], v[120:121], v[128:129]
	v_pk_fma_f32 v[130:131], v[10:11], v[122:123], v[130:131]
	v_pk_fma_f32 v[124:125], v[12:13], v[132:133], v[124:125]
	v_pk_fma_f32 v[126:127], v[8:9], v[134:135], v[126:127]
	s_waitcnt lgkmcnt(4)
	v_lshlrev_b32_e32 v132, 16, v226
	v_and_b32_e32 v133, 0xffff0000, v226
	v_lshlrev_b32_e32 v120, 16, v227
	v_and_b32_e32 v121, 0xffff0000, v227
	v_lshlrev_b32_e32 v134, 16, v228
	v_and_b32_e32 v135, 0xffff0000, v228
	v_lshlrev_b32_e32 v122, 16, v229
	v_and_b32_e32 v123, 0xffff0000, v229
	v_pk_fma_f32 v[124:125], v[24:25], v[132:133], v[124:125]
	v_pk_fma_f32 v[128:129], v[26:27], v[120:121], v[128:129]
	v_pk_fma_f32 v[132:133], v[28:29], v[134:135], v[126:127]
	v_pk_fma_f32 v[126:127], v[30:31], v[122:123], v[130:131]
	s_waitcnt lgkmcnt(3)
	v_lshlrev_b32_e32 v130, 16, v230
	v_and_b32_e32 v131, 0xffff0000, v230
	v_lshlrev_b32_e32 v120, 16, v231
	v_and_b32_e32 v121, 0xffff0000, v231
	v_lshlrev_b32_e32 v134, 16, v232
	v_and_b32_e32 v135, 0xffff0000, v232
	v_lshlrev_b32_e32 v136, 16, v233
	v_and_b32_e32 v137, 0xffff0000, v233
	v_pk_fma_f32 v[122:123], v[34:35], v[120:121], v[128:129]
	v_pk_fma_f32 v[120:121], v[32:33], v[130:131], v[124:125]
	v_pk_fma_f32 v[126:127], v[38:39], v[136:137], v[126:127]
	v_pk_fma_f32 v[124:125], v[36:37], v[134:135], v[132:133]
	ds_write_b128 v179, v[120:123] offset:4480
	ds_write_b128 v179, v[124:127] offset:4496
	v_cvt_pk_bf16_f32 v120, v120, v121
	v_cvt_pk_bf16_f32 v121, v122, v123
	v_cvt_pk_bf16_f32 v122, v124, v125
	v_cvt_pk_bf16_f32 v123, v126, v127
	ds_write_b128 v180, v[120:123] offset:1152
	s_waitcnt lgkmcnt(0)
	s_mov_b32 s0, 0x37d00d01
	s_mov_b32 s1, 0x37d00d01
	s_mov_b32 s80, 0x3ab60b61
	s_mov_b32 s81, 0x3ab60b61
	s_mov_b32 s82, 0x3c088889
	s_mov_b32 s83, 0x3c088889
	s_mov_b32 s84, 0x3d2aaaab
	s_mov_b32 s85, 0x3d2aaaab
	ds_read_b128 v[120:123], v173
	ds_read_b128 v[222:225], v173 offset:64
	v_mov_b32_e32 v168, 1.0
	v_mov_b32_e32 v232, 0xbfb8aa3b
	v_add_u32_e32 v233, 2304, v175
	s_waitcnt lgkmcnt(0)
	v_mfma_f32_16x16x32_bf16 v[128:131], v[120:123], v[40:43], 0
	v_mfma_f32_16x16x32_bf16 v[132:135], v[120:123], v[72:75], 0
	v_mfma_f32_16x16x32_bf16 v[128:131], v[222:225], v[44:47], v[128:131]
	v_mfma_f32_16x16x32_bf16 v[132:135], v[222:225], v[76:79], v[132:135]
	v_mfma_f32_16x16x32_bf16 v[136:139], v[120:123], v[48:51], 0
	v_mfma_f32_16x16x32_bf16 v[140:143], v[120:123], v[80:83], 0
	v_mfma_f32_16x16x32_bf16 v[136:139], v[222:225], v[52:55], v[136:139]
	v_mfma_f32_16x16x32_bf16 v[140:143], v[222:225], v[84:87], v[140:143]
	s_nop 7
	ds_read2_b32 v[230:231], v233 offset0:0 offset1:68
	v_add_f32_e64 v124, v128, v161
	v_add_f32_e64 v125, v129, v161
	v_add_f32_e64 v126, v132, v163
	v_add_f32_e64 v127, v133, v163
	v_pk_mul_f32 v[124:125], v[124:125], v[232:233] op_sel_hi:[1,0]
	v_pk_mul_f32 v[126:127], v[126:127], v[232:233] op_sel_hi:[1,0]
	v_exp_f32_e32 v124, v124
	v_exp_f32_e32 v125, v125
	v_exp_f32_e32 v126, v126
	v_exp_f32_e32 v127, v127
	v_pk_add_f32 v[124:125], v[124:125], v[168:169] op_sel_hi:[1,0]
	v_pk_add_f32 v[126:127], v[126:127], v[168:169] op_sel_hi:[1,0]
	v_rcp_f32_e32 v124, v124
	v_rcp_f32_e32 v125, v125
	v_rcp_f32_e32 v126, v126
	v_rcp_f32_e32 v127, v127
	v_pk_mul_f32 v[170:171], v[124:125], v[98:99] op_sel_hi:[1,0]
	v_mul_f32_e32 v226, 0x3fb8aa3b, v170
	v_mul_f32_e32 v227, 0x3fb8aa3b, v171
	v_pk_add_f32 v[170:171], v[170:171], v[170:171]
	v_exp_f32_e32 v226, v226
	v_exp_f32_e32 v227, v227
	v_pk_fma_f32 v[228:229], v[170:171], s[0:1], v[198:199] op_sel_hi:[1,1,0]
	v_pk_fma_f32 v[228:229], v[170:171], v[228:229], s[80:81]
	v_pk_fma_f32 v[228:229], v[170:171], v[228:229], s[82:83]
	v_pk_fma_f32 v[228:229], v[170:171], v[228:229], s[84:85]
	v_fmaak_f32 v228, v170, v228, 0x3e2aaaab
	v_fmaak_f32 v229, v171, v229, 0x3e2aaaab
	v_fma_f32 v228, v170, v228, 0.5
	v_fma_f32 v229, v171, v229, 0.5
	v_pk_fma_f32 v[228:229], v[170:171], v[228:229], v[168:169] op_sel_hi:[1,1,0]
	v_pk_mul_f32 v[228:229], v[170:171], v[228:229] neg_lo:[0,1] neg_hi:[0,1]
	v_max_f32_e32 v228, 0, v228
	v_max_f32_e32 v229, 0, v229
	v_sqrt_f32_e32 v228, v228
	v_sqrt_f32_e32 v229, v229
	ds_write_b32 v175, v226 offset:6656
	ds_write_b32 v175, v227 offset:6928
	v_pk_mul_f32 v[228:229], v[126:127], v[228:229]
	s_waitcnt lgkmcnt(2)
	v_pk_mul_f32 v[228:229], v[230:231], v[228:229]
	ds_write2_b32 v233, v228, v229 offset0:0 offset1:68
	ds_read2_b32 v[230:231], v233 offset0:136 offset1:204
	v_add_f32_e64 v124, v130, v161
	v_add_f32_e64 v125, v131, v161
	v_add_f32_e64 v126, v134, v163
	v_add_f32_e64 v127, v135, v163
	v_pk_mul_f32 v[124:125], v[124:125], v[232:233] op_sel_hi:[1,0]
	v_pk_mul_f32 v[126:127], v[126:127], v[232:233] op_sel_hi:[1,0]
	v_exp_f32_e32 v124, v124
	v_exp_f32_e32 v125, v125
	v_exp_f32_e32 v126, v126
	v_exp_f32_e32 v127, v127
	v_pk_add_f32 v[124:125], v[124:125], v[168:169] op_sel_hi:[1,0]
	v_pk_add_f32 v[126:127], v[126:127], v[168:169] op_sel_hi:[1,0]
	v_rcp_f32_e32 v124, v124
	v_rcp_f32_e32 v125, v125
	v_rcp_f32_e32 v126, v126
	v_rcp_f32_e32 v127, v127
	v_pk_mul_f32 v[170:171], v[124:125], v[98:99] op_sel_hi:[1,0]
	v_mul_f32_e32 v226, 0x3fb8aa3b, v170
	v_mul_f32_e32 v227, 0x3fb8aa3b, v171
	v_pk_add_f32 v[170:171], v[170:171], v[170:171]
	v_exp_f32_e32 v226, v226
	v_exp_f32_e32 v227, v227
	v_pk_fma_f32 v[228:229], v[170:171], s[0:1], v[198:199] op_sel_hi:[1,1,0]
	v_pk_fma_f32 v[228:229], v[170:171], v[228:229], s[80:81]
	v_pk_fma_f32 v[228:229], v[170:171], v[228:229], s[82:83]
	v_pk_fma_f32 v[228:229], v[170:171], v[228:229], s[84:85]
	v_fmaak_f32 v228, v170, v228, 0x3e2aaaab
	v_fmaak_f32 v229, v171, v229, 0x3e2aaaab
	v_fma_f32 v228, v170, v228, 0.5
	v_fma_f32 v229, v171, v229, 0.5
	v_pk_fma_f32 v[228:229], v[170:171], v[228:229], v[168:169] op_sel_hi:[1,1,0]
	v_pk_mul_f32 v[228:229], v[170:171], v[228:229] neg_lo:[0,1] neg_hi:[0,1]
	v_max_f32_e32 v228, 0, v228
	v_max_f32_e32 v229, 0, v229
	v_sqrt_f32_e32 v228, v228
	v_sqrt_f32_e32 v229, v229
	ds_write_b32 v175, v226 offset:7200
	ds_write_b32 v175, v227 offset:7472
	v_pk_mul_f32 v[228:229], v[126:127], v[228:229]
	s_waitcnt lgkmcnt(2)
	v_pk_mul_f32 v[228:229], v[230:231], v[228:229]
	ds_write2_b32 v233, v228, v229 offset0:136 offset1:204
	v_mfma_f32_16x16x32_bf16 v[128:131], v[120:123], v[56:59], 0
	v_mfma_f32_16x16x32_bf16 v[132:135], v[120:123], v[88:91], 0
	v_mfma_f32_16x16x32_bf16 v[128:131], v[222:225], v[60:63], v[128:131]
	v_mfma_f32_16x16x32_bf16 v[132:135], v[222:225], v[92:95], v[132:135]
	ds_read2_b32 v[230:231], v233 offset0:16 offset1:84
	v_add_f32_e64 v124, v136, v181
	v_add_f32_e64 v125, v137, v181
	v_pk_add_f32 v[126:127], v[140:141], v[188:189] op_sel_hi:[1,0]
	v_pk_mul_f32 v[124:125], v[124:125], v[232:233] op_sel_hi:[1,0]
	v_pk_mul_f32 v[126:127], v[126:127], v[232:233] op_sel_hi:[1,0]
	v_exp_f32_e32 v124, v124
	v_exp_f32_e32 v125, v125
	v_exp_f32_e32 v126, v126
	v_exp_f32_e32 v127, v127
	v_pk_add_f32 v[124:125], v[124:125], v[168:169] op_sel_hi:[1,0]
	v_pk_add_f32 v[126:127], v[126:127], v[168:169] op_sel_hi:[1,0]
	v_rcp_f32_e32 v124, v124
	v_rcp_f32_e32 v125, v125
	v_rcp_f32_e32 v126, v126
	v_rcp_f32_e32 v127, v127
	v_mul_f32_e64 v170, v124, v193
	v_mul_f32_e64 v171, v125, v193
	v_mul_f32_e32 v226, 0x3fb8aa3b, v170
	v_mul_f32_e32 v227, 0x3fb8aa3b, v171
	v_pk_add_f32 v[170:171], v[170:171], v[170:171]
	v_exp_f32_e32 v226, v226
	v_exp_f32_e32 v227, v227
	v_pk_fma_f32 v[228:229], v[170:171], s[0:1], v[198:199] op_sel_hi:[1,1,0]
	v_pk_fma_f32 v[228:229], v[170:171], v[228:229], s[80:81]
	v_pk_fma_f32 v[228:229], v[170:171], v[228:229], s[82:83]
	v_pk_fma_f32 v[228:229], v[170:171], v[228:229], s[84:85]
	v_fmaak_f32 v228, v170, v228, 0x3e2aaaab
	v_fmaak_f32 v229, v171, v229, 0x3e2aaaab
	v_fma_f32 v228, v170, v228, 0.5
	v_fma_f32 v229, v171, v229, 0.5
	v_pk_fma_f32 v[228:229], v[170:171], v[228:229], v[168:169] op_sel_hi:[1,1,0]
	v_pk_mul_f32 v[228:229], v[170:171], v[228:229] neg_lo:[0,1] neg_hi:[0,1]
	v_max_f32_e32 v228, 0, v228
	v_max_f32_e32 v229, 0, v229
	v_sqrt_f32_e32 v228, v228
	v_sqrt_f32_e32 v229, v229
	ds_write_b32 v175, v226 offset:6720
	ds_write_b32 v175, v227 offset:6992
	v_pk_mul_f32 v[228:229], v[126:127], v[228:229]
	s_waitcnt lgkmcnt(2)
	v_pk_mul_f32 v[228:229], v[230:231], v[228:229]
	ds_write2_b32 v233, v228, v229 offset0:16 offset1:84
	ds_read2_b32 v[230:231], v233 offset0:152 offset1:220
	v_add_f32_e64 v124, v138, v181
	v_add_f32_e64 v125, v139, v181
	v_pk_add_f32 v[126:127], v[142:143], v[188:189] op_sel_hi:[1,0]
	v_pk_mul_f32 v[124:125], v[124:125], v[232:233] op_sel_hi:[1,0]
	v_pk_mul_f32 v[126:127], v[126:127], v[232:233] op_sel_hi:[1,0]
	v_exp_f32_e32 v124, v124
	v_exp_f32_e32 v125, v125
	v_exp_f32_e32 v126, v126
	v_exp_f32_e32 v127, v127
	v_pk_add_f32 v[124:125], v[124:125], v[168:169] op_sel_hi:[1,0]
	v_pk_add_f32 v[126:127], v[126:127], v[168:169] op_sel_hi:[1,0]
	v_rcp_f32_e32 v124, v124
	v_rcp_f32_e32 v125, v125
	v_rcp_f32_e32 v126, v126
	v_rcp_f32_e32 v127, v127
	v_mul_f32_e64 v170, v124, v193
	v_mul_f32_e64 v171, v125, v193
	v_mul_f32_e32 v226, 0x3fb8aa3b, v170
	v_mul_f32_e32 v227, 0x3fb8aa3b, v171
	v_pk_add_f32 v[170:171], v[170:171], v[170:171]
	v_exp_f32_e32 v226, v226
	v_exp_f32_e32 v227, v227
	v_pk_fma_f32 v[228:229], v[170:171], s[0:1], v[198:199] op_sel_hi:[1,1,0]
	v_pk_fma_f32 v[228:229], v[170:171], v[228:229], s[80:81]
	v_pk_fma_f32 v[228:229], v[170:171], v[228:229], s[82:83]
	v_pk_fma_f32 v[228:229], v[170:171], v[228:229], s[84:85]
	v_fmaak_f32 v228, v170, v228, 0x3e2aaaab
	v_fmaak_f32 v229, v171, v229, 0x3e2aaaab
	v_fma_f32 v228, v170, v228, 0.5
	v_fma_f32 v229, v171, v229, 0.5
	v_pk_fma_f32 v[228:229], v[170:171], v[228:229], v[168:169] op_sel_hi:[1,1,0]
	v_pk_mul_f32 v[228:229], v[170:171], v[228:229] neg_lo:[0,1] neg_hi:[0,1]
	v_max_f32_e32 v228, 0, v228
	v_max_f32_e32 v229, 0, v229
	v_sqrt_f32_e32 v228, v228
	v_sqrt_f32_e32 v229, v229
	ds_write_b32 v175, v226 offset:7264
	ds_write_b32 v175, v227 offset:7536
	v_pk_mul_f32 v[228:229], v[126:127], v[228:229]
	s_waitcnt lgkmcnt(2)
	v_pk_mul_f32 v[228:229], v[230:231], v[228:229]
	ds_write2_b32 v233, v228, v229 offset0:152 offset1:220
	v_mfma_f32_16x16x32_bf16 v[136:139], v[120:123], v[64:67], 0
	v_mfma_f32_16x16x32_bf16 v[140:143], v[120:123], v[100:103], 0
	v_mfma_f32_16x16x32_bf16 v[136:139], v[222:225], v[68:71], v[136:139]
	v_mfma_f32_16x16x32_bf16 v[140:143], v[222:225], v[104:107], v[140:143]
	ds_read2_b32 v[230:231], v233 offset0:32 offset1:100
	v_add_f32_e64 v124, v128, v189
	v_add_f32_e64 v125, v129, v189
	v_pk_add_f32 v[126:127], v[132:133], v[190:191] op_sel_hi:[1,0]
	v_pk_mul_f32 v[124:125], v[124:125], v[232:233] op_sel_hi:[1,0]
	v_pk_mul_f32 v[126:127], v[126:127], v[232:233] op_sel_hi:[1,0]
	v_exp_f32_e32 v124, v124
	v_exp_f32_e32 v125, v125
	v_exp_f32_e32 v126, v126
	v_exp_f32_e32 v127, v127
	v_pk_add_f32 v[124:125], v[124:125], v[168:169] op_sel_hi:[1,0]
	v_pk_add_f32 v[126:127], v[126:127], v[168:169] op_sel_hi:[1,0]
	v_rcp_f32_e32 v124, v124
	v_rcp_f32_e32 v125, v125
	v_rcp_f32_e32 v126, v126
	v_rcp_f32_e32 v127, v127
	v_pk_mul_f32 v[170:171], v[124:125], v[220:221] op_sel_hi:[1,0]
	v_mul_f32_e32 v226, 0x3fb8aa3b, v170
	v_mul_f32_e32 v227, 0x3fb8aa3b, v171
	v_pk_add_f32 v[170:171], v[170:171], v[170:171]
	v_exp_f32_e32 v226, v226
	v_exp_f32_e32 v227, v227
	v_pk_fma_f32 v[228:229], v[170:171], s[0:1], v[198:199] op_sel_hi:[1,1,0]
	v_pk_fma_f32 v[228:229], v[170:171], v[228:229], s[80:81]
	v_pk_fma_f32 v[228:229], v[170:171], v[228:229], s[82:83]
	v_pk_fma_f32 v[228:229], v[170:171], v[228:229], s[84:85]
	v_fmaak_f32 v228, v170, v228, 0x3e2aaaab
	v_fmaak_f32 v229, v171, v229, 0x3e2aaaab
	v_fma_f32 v228, v170, v228, 0.5
	v_fma_f32 v229, v171, v229, 0.5
	v_pk_fma_f32 v[228:229], v[170:171], v[228:229], v[168:169] op_sel_hi:[1,1,0]
	v_pk_mul_f32 v[228:229], v[170:171], v[228:229] neg_lo:[0,1] neg_hi:[0,1]
	v_max_f32_e32 v228, 0, v228
	v_max_f32_e32 v229, 0, v229
	v_sqrt_f32_e32 v228, v228
	v_sqrt_f32_e32 v229, v229
	ds_write_b32 v175, v226 offset:6784
	ds_write_b32 v175, v227 offset:7056
	v_pk_mul_f32 v[228:229], v[126:127], v[228:229]
	s_waitcnt lgkmcnt(2)
	v_pk_mul_f32 v[228:229], v[230:231], v[228:229]
	ds_write2_b32 v233, v228, v229 offset0:32 offset1:100
	ds_read2_b32 v[230:231], v233 offset0:168 offset1:236
	v_add_f32_e64 v124, v130, v189
	v_add_f32_e64 v125, v131, v189
	v_pk_add_f32 v[126:127], v[134:135], v[190:191] op_sel_hi:[1,0]
	v_pk_mul_f32 v[124:125], v[124:125], v[232:233] op_sel_hi:[1,0]
	v_pk_mul_f32 v[126:127], v[126:127], v[232:233] op_sel_hi:[1,0]
	v_exp_f32_e32 v124, v124
	v_exp_f32_e32 v125, v125
	v_exp_f32_e32 v126, v126
	v_exp_f32_e32 v127, v127
	v_pk_add_f32 v[124:125], v[124:125], v[168:169] op_sel_hi:[1,0]
	v_pk_add_f32 v[126:127], v[126:127], v[168:169] op_sel_hi:[1,0]
	v_rcp_f32_e32 v124, v124
	v_rcp_f32_e32 v125, v125
	v_rcp_f32_e32 v126, v126
	v_rcp_f32_e32 v127, v127
	v_pk_mul_f32 v[170:171], v[124:125], v[220:221] op_sel_hi:[1,0]
	v_mul_f32_e32 v226, 0x3fb8aa3b, v170
	v_mul_f32_e32 v227, 0x3fb8aa3b, v171
	v_pk_add_f32 v[170:171], v[170:171], v[170:171]
	v_exp_f32_e32 v226, v226
	v_exp_f32_e32 v227, v227
	v_pk_fma_f32 v[228:229], v[170:171], s[0:1], v[198:199] op_sel_hi:[1,1,0]
	v_pk_fma_f32 v[228:229], v[170:171], v[228:229], s[80:81]
	v_pk_fma_f32 v[228:229], v[170:171], v[228:229], s[82:83]
	v_pk_fma_f32 v[228:229], v[170:171], v[228:229], s[84:85]
	v_fmaak_f32 v228, v170, v228, 0x3e2aaaab
	v_fmaak_f32 v229, v171, v229, 0x3e2aaaab
	v_fma_f32 v228, v170, v228, 0.5
	v_fma_f32 v229, v171, v229, 0.5
	v_pk_fma_f32 v[228:229], v[170:171], v[228:229], v[168:169] op_sel_hi:[1,1,0]
	v_pk_mul_f32 v[228:229], v[170:171], v[228:229] neg_lo:[0,1] neg_hi:[0,1]
	v_max_f32_e32 v228, 0, v228
	v_max_f32_e32 v229, 0, v229
	v_sqrt_f32_e32 v228, v228
	v_sqrt_f32_e32 v229, v229
	ds_write_b32 v175, v226 offset:7328
	ds_write_b32 v175, v227 offset:7600
	v_pk_mul_f32 v[228:229], v[126:127], v[228:229]
	s_waitcnt lgkmcnt(2)
	v_pk_mul_f32 v[228:229], v[230:231], v[228:229]
	ds_write2_b32 v233, v228, v229 offset0:168 offset1:236
	ds_read2_b32 v[230:231], v233 offset0:48 offset1:116
	v_pk_add_f32 v[124:125], v[136:137], v[192:193] op_sel_hi:[1,0]
	v_add_f32_e64 v126, v140, v191
	v_add_f32_e64 v127, v141, v191
	v_pk_mul_f32 v[124:125], v[124:125], v[232:233] op_sel_hi:[1,0]
	v_pk_mul_f32 v[126:127], v[126:127], v[232:233] op_sel_hi:[1,0]
	v_exp_f32_e32 v124, v124
	v_exp_f32_e32 v125, v125
	v_exp_f32_e32 v126, v126
	v_exp_f32_e32 v127, v127
	v_pk_add_f32 v[124:125], v[124:125], v[168:169] op_sel_hi:[1,0]
	v_pk_add_f32 v[126:127], v[126:127], v[168:169] op_sel_hi:[1,0]
	v_rcp_f32_e32 v124, v124
	v_rcp_f32_e32 v125, v125
	v_rcp_f32_e32 v126, v126
	v_rcp_f32_e32 v127, v127
	v_mul_f32_e64 v170, v124, v221
	v_mul_f32_e64 v171, v125, v221
	v_mul_f32_e32 v226, 0x3fb8aa3b, v170
	v_mul_f32_e32 v227, 0x3fb8aa3b, v171
	v_pk_add_f32 v[170:171], v[170:171], v[170:171]
	v_exp_f32_e32 v226, v226
	v_exp_f32_e32 v227, v227
	v_pk_fma_f32 v[228:229], v[170:171], s[0:1], v[198:199] op_sel_hi:[1,1,0]
	v_pk_fma_f32 v[228:229], v[170:171], v[228:229], s[80:81]
	v_pk_fma_f32 v[228:229], v[170:171], v[228:229], s[82:83]
	v_pk_fma_f32 v[228:229], v[170:171], v[228:229], s[84:85]
	v_fmaak_f32 v228, v170, v228, 0x3e2aaaab
	v_fmaak_f32 v229, v171, v229, 0x3e2aaaab
	v_fma_f32 v228, v170, v228, 0.5
	v_fma_f32 v229, v171, v229, 0.5
	v_pk_fma_f32 v[228:229], v[170:171], v[228:229], v[168:169] op_sel_hi:[1,1,0]
	v_pk_mul_f32 v[228:229], v[170:171], v[228:229] neg_lo:[0,1] neg_hi:[0,1]
	v_max_f32_e32 v228, 0, v228
	v_max_f32_e32 v229, 0, v229
	v_sqrt_f32_e32 v228, v228
	v_sqrt_f32_e32 v229, v229
	ds_write_b32 v175, v226 offset:6848
	ds_write_b32 v175, v227 offset:7120
	v_pk_mul_f32 v[228:229], v[126:127], v[228:229]
	s_waitcnt lgkmcnt(2)
	v_pk_mul_f32 v[228:229], v[230:231], v[228:229]
	ds_write2_b32 v233, v228, v229 offset0:48 offset1:116
	ds_read2_b32 v[230:231], v233 offset0:184 offset1:252
	v_pk_add_f32 v[124:125], v[138:139], v[192:193] op_sel_hi:[1,0]
	v_add_f32_e64 v126, v142, v191
	v_add_f32_e64 v127, v143, v191
	v_pk_mul_f32 v[124:125], v[124:125], v[232:233] op_sel_hi:[1,0]
	v_pk_mul_f32 v[126:127], v[126:127], v[232:233] op_sel_hi:[1,0]
	v_exp_f32_e32 v124, v124
	v_exp_f32_e32 v125, v125
	v_exp_f32_e32 v126, v126
	v_exp_f32_e32 v127, v127
	v_pk_add_f32 v[124:125], v[124:125], v[168:169] op_sel_hi:[1,0]
	v_pk_add_f32 v[126:127], v[126:127], v[168:169] op_sel_hi:[1,0]
	v_rcp_f32_e32 v124, v124
	v_rcp_f32_e32 v125, v125
	v_rcp_f32_e32 v126, v126
	v_rcp_f32_e32 v127, v127
	v_mul_f32_e64 v170, v124, v221
	v_mul_f32_e64 v171, v125, v221
	v_mul_f32_e32 v226, 0x3fb8aa3b, v170
	v_mul_f32_e32 v227, 0x3fb8aa3b, v171
	v_pk_add_f32 v[170:171], v[170:171], v[170:171]
	v_exp_f32_e32 v226, v226
	v_exp_f32_e32 v227, v227
	v_pk_fma_f32 v[228:229], v[170:171], s[0:1], v[198:199] op_sel_hi:[1,1,0]
	v_pk_fma_f32 v[228:229], v[170:171], v[228:229], s[80:81]
	v_pk_fma_f32 v[228:229], v[170:171], v[228:229], s[82:83]
	v_pk_fma_f32 v[228:229], v[170:171], v[228:229], s[84:85]
	v_fmaak_f32 v228, v170, v228, 0x3e2aaaab
	v_fmaak_f32 v229, v171, v229, 0x3e2aaaab
	v_fma_f32 v228, v170, v228, 0.5
	v_fma_f32 v229, v171, v229, 0.5
	v_pk_fma_f32 v[228:229], v[170:171], v[228:229], v[168:169] op_sel_hi:[1,1,0]
	v_pk_mul_f32 v[228:229], v[170:171], v[228:229] neg_lo:[0,1] neg_hi:[0,1]
	v_max_f32_e32 v228, 0, v228
	v_max_f32_e32 v229, 0, v229
	v_sqrt_f32_e32 v228, v228
	v_sqrt_f32_e32 v229, v229
	ds_write_b32 v175, v226 offset:7392
	ds_write_b32 v175, v227 offset:7664
	v_pk_mul_f32 v[228:229], v[126:127], v[228:229]
	s_waitcnt lgkmcnt(2)
	v_pk_mul_f32 v[228:229], v[230:231], v[228:229]
	ds_write2_b32 v233, v228, v229 offset0:184 offset1:252
	v_add_u32_e32 v126, 0x1c00, v174
	s_waitcnt lgkmcnt(0)
	v_add_u32_e32 v165, 6656, v174
	v_add_u32_e32 v168, 2304, v174
	ds_read2_b32 v[120:121], v165 offset0:0 offset1:68
	ds_read2_b32 v[122:123], v168 offset0:0 offset1:68
	ds_read2_b32 v[124:125], v165 offset0:136 offset1:204
	ds_read2_b32 v[126:127], v168 offset0:136 offset1:204
	v_add_u32_e32 v165, 7744, v174
	v_add_u32_e32 v168, 3392, v174
	ds_read2_b32 v[128:129], v165 offset0:0 offset1:68
	ds_read2_b32 v[130:131], v168 offset0:0 offset1:68
	ds_read2_b32 v[132:133], v165 offset0:136 offset1:204
	ds_read2_b32 v[134:135], v168 offset0:136 offset1:204
	v_add_u32_e32 v165, 8832, v174
	v_add_u32_e32 v168, 4480, v174
	ds_read2_b32 v[136:137], v165 offset0:0 offset1:68
	ds_read2_b32 v[138:139], v168 offset0:0 offset1:68
	ds_read2_b32 v[140:141], v165 offset0:136 offset1:204
	ds_read2_b32 v[142:143], v168 offset0:136 offset1:204
	v_add_u32_e32 v165, 9920, v174
	v_add_u32_e32 v168, 5568, v174
	ds_read2_b32 v[170:171], v165 offset0:0 offset1:68
	ds_read2_b32 v[222:223], v168 offset0:0 offset1:68
	ds_read2_b32 v[224:225], v165 offset0:136 offset1:204
	ds_read2_b32 v[226:227], v168 offset0:136 offset1:204
	s_waitcnt lgkmcnt(14)
	v_fma_f32 v164, v164, v120, v122
	v_mul_f32_e32 v169, v169, v120
	v_fma_f32 v164, v164, v121, v123
	v_mul_f32_e32 v169, v169, v121
	s_waitcnt lgkmcnt(12)
	v_fma_f32 v164, v164, v124, v126
	v_mul_f32_e32 v169, v169, v124
	v_fma_f32 v164, v164, v125, v127
	v_mul_f32_e32 v169, v169, v125
	s_waitcnt lgkmcnt(10)
	v_fma_f32 v164, v164, v128, v130
	v_mul_f32_e32 v169, v169, v128
	v_fma_f32 v164, v164, v129, v131
	v_mul_f32_e32 v169, v169, v129
	s_waitcnt lgkmcnt(8)
	v_fma_f32 v164, v164, v132, v134
	v_mul_f32_e32 v169, v169, v132
	v_fma_f32 v164, v164, v133, v135
	v_mul_f32_e32 v169, v169, v133
	s_waitcnt lgkmcnt(6)
	v_fma_f32 v164, v164, v136, v138
	v_mul_f32_e32 v169, v169, v136
	v_fma_f32 v164, v164, v137, v139
	v_mul_f32_e32 v169, v169, v137
	s_waitcnt lgkmcnt(4)
	v_fma_f32 v164, v164, v140, v142
	v_mul_f32_e32 v169, v169, v140
	v_fma_f32 v164, v164, v141, v143
	v_mul_f32_e32 v169, v169, v141
	s_waitcnt lgkmcnt(2)
	v_fma_f32 v164, v164, v170, v222
	v_mul_f32_e32 v169, v169, v170
	v_fma_f32 v164, v164, v171, v223
	v_mul_f32_e32 v169, v169, v171
	s_waitcnt lgkmcnt(0)
	v_fma_f32 v164, v164, v224, v226
	v_mul_f32_e32 v169, v169, v224
	v_fma_f32 v164, v164, v225, v227
	v_mul_f32_e32 v169, v169, v225
	s_cbranch_scc0 .LBB0_194

.LBB0_274:
	v_add_co_u32_e32 v120, vcc, 0x1200b000, v120
	v_lshl_add_u64 v[122:123], v[190:191], 0, v[166:167]
	s_nop 0
	v_addc_co_u32_e32 v121, vcc, 0, v121, vcc
	global_load_dwordx4 v[124:127], v[122:123], off
	s_add_i32 s20, s20, -1
	global_load_dwordx4 v[120:123], v[120:121], off
	s_waitcnt lgkmcnt(0)
	ds_read_b128 v[146:149], v229 offset:11008
	ds_read_b128 v[240:243], v229 offset:11152
	ds_read_b128 v[244:247], v229 offset:11296
	ds_read_b128 v[248:251], v229 offset:11440
	v_lshl_add_u64 v[180:181], v[180:181], 0, s[62:63]
	v_lshl_add_u64 v[190:191], v[190:191], 0, s[62:63]
	s_cmp_lg_u32 s20, 0
	s_waitcnt lgkmcnt(3)
	v_lshlrev_b32_e32 v132, 16, v146
	v_and_b32_e32 v133, 0xffff0000, v146
	v_lshlrev_b32_e32 v128, 16, v147
	v_and_b32_e32 v129, 0xffff0000, v147
	v_lshlrev_b32_e32 v134, 16, v148
	v_and_b32_e32 v135, 0xffff0000, v148
	v_lshlrev_b32_e32 v130, 16, v149
	v_and_b32_e32 v131, 0xffff0000, v149
	ds_read_b128 v[146:149], v229 offset:12160
	v_pk_fma_f32 v[136:137], v[6:7], v[128:129], v[22:23]
	v_pk_fma_f32 v[138:139], v[2:3], v[130:131], v[18:19]
	v_pk_fma_f32 v[132:133], v[4:5], v[132:133], v[20:21]
	v_pk_fma_f32 v[134:135], v[0:1], v[134:135], v[16:17]
	s_waitcnt lgkmcnt(3)
	v_lshlrev_b32_e32 v140, 16, v240
	v_and_b32_e32 v141, 0xffff0000, v240
	v_lshlrev_b32_e32 v128, 16, v241
	v_and_b32_e32 v129, 0xffff0000, v241
	v_lshlrev_b32_e32 v142, 16, v242
	v_and_b32_e32 v143, 0xffff0000, v242
	v_lshlrev_b32_e32 v130, 16, v243
	v_and_b32_e32 v131, 0xffff0000, v243
	ds_read_b128 v[240:243], v229 offset:12304
	v_pk_fma_f32 v[136:137], v[14:15], v[128:129], v[136:137]
	v_pk_fma_f32 v[138:139], v[10:11], v[130:131], v[138:139]
	v_pk_fma_f32 v[132:133], v[12:13], v[140:141], v[132:133]
	v_pk_fma_f32 v[134:135], v[8:9], v[142:143], v[134:135]
	s_waitcnt lgkmcnt(3)
	v_lshlrev_b32_e32 v140, 16, v244
	v_and_b32_e32 v141, 0xffff0000, v244
	v_lshlrev_b32_e32 v128, 16, v245
	v_and_b32_e32 v129, 0xffff0000, v245
	v_lshlrev_b32_e32 v142, 16, v246
	v_and_b32_e32 v143, 0xffff0000, v246
	v_lshlrev_b32_e32 v130, 16, v247
	v_and_b32_e32 v131, 0xffff0000, v247
	ds_read_b128 v[244:247], v229 offset:12448
	v_pk_fma_f32 v[132:133], v[24:25], v[140:141], v[132:133]
	v_pk_fma_f32 v[136:137], v[26:27], v[128:129], v[136:137]
	v_pk_fma_f32 v[140:141], v[28:29], v[142:143], v[134:135]
	v_pk_fma_f32 v[134:135], v[30:31], v[130:131], v[138:139]
	s_waitcnt lgkmcnt(3)
	v_lshlrev_b32_e32 v138, 16, v248
	v_and_b32_e32 v139, 0xffff0000, v248
	v_lshlrev_b32_e32 v128, 16, v249
	v_and_b32_e32 v129, 0xffff0000, v249
	v_lshlrev_b32_e32 v142, 16, v250
	v_and_b32_e32 v143, 0xffff0000, v250
	v_lshlrev_b32_e32 v144, 16, v251
	v_and_b32_e32 v145, 0xffff0000, v251
	ds_read_b128 v[248:251], v229 offset:12592
	v_pk_fma_f32 v[130:131], v[34:35], v[128:129], v[136:137]
	v_pk_fma_f32 v[128:129], v[32:33], v[138:139], v[132:133]
	v_pk_fma_f32 v[134:135], v[38:39], v[144:145], v[134:135]
	v_pk_fma_f32 v[132:133], v[36:37], v[142:143], v[140:141]
	ds_write_b128 v228, v[128:131] offset:2304
	ds_write_b128 v228, v[132:135] offset:2320
	v_cvt_pk_bf16_f32 v128, v128, v129
	v_cvt_pk_bf16_f32 v129, v130, v131
	v_cvt_pk_bf16_f32 v130, v132, v133
	v_cvt_pk_bf16_f32 v131, v134, v135
	ds_write_b128 v229, v[128:131]
	s_waitcnt lgkmcnt(6)
	v_lshlrev_b32_e32 v132, 16, v146
	v_and_b32_e32 v133, 0xffff0000, v146
	v_lshlrev_b32_e32 v128, 16, v147
	v_and_b32_e32 v129, 0xffff0000, v147
	v_lshlrev_b32_e32 v134, 16, v148
	v_and_b32_e32 v135, 0xffff0000, v148
	v_lshlrev_b32_e32 v130, 16, v149
	v_and_b32_e32 v131, 0xffff0000, v149
	v_pk_fma_f32 v[136:137], v[6:7], v[128:129], v[22:23]
	v_pk_fma_f32 v[138:139], v[2:3], v[130:131], v[18:19]
	v_pk_fma_f32 v[132:133], v[4:5], v[132:133], v[20:21]
	v_pk_fma_f32 v[134:135], v[0:1], v[134:135], v[16:17]
	s_waitcnt lgkmcnt(5)
	v_lshlrev_b32_e32 v140, 16, v240
	v_and_b32_e32 v141, 0xffff0000, v240
	v_lshlrev_b32_e32 v128, 16, v241
	v_and_b32_e32 v129, 0xffff0000, v241
	v_lshlrev_b32_e32 v142, 16, v242
	v_and_b32_e32 v143, 0xffff0000, v242
	v_lshlrev_b32_e32 v130, 16, v243
	v_and_b32_e32 v131, 0xffff0000, v243
	v_pk_fma_f32 v[136:137], v[14:15], v[128:129], v[136:137]
	v_pk_fma_f32 v[138:139], v[10:11], v[130:131], v[138:139]
	v_pk_fma_f32 v[132:133], v[12:13], v[140:141], v[132:133]
	v_pk_fma_f32 v[134:135], v[8:9], v[142:143], v[134:135]
	s_waitcnt lgkmcnt(4)
	v_lshlrev_b32_e32 v140, 16, v244
	v_and_b32_e32 v141, 0xffff0000, v244
	v_lshlrev_b32_e32 v128, 16, v245
	v_and_b32_e32 v129, 0xffff0000, v245
	v_lshlrev_b32_e32 v142, 16, v246
	v_and_b32_e32 v143, 0xffff0000, v246
	v_lshlrev_b32_e32 v130, 16, v247
	v_and_b32_e32 v131, 0xffff0000, v247
	v_pk_fma_f32 v[132:133], v[24:25], v[140:141], v[132:133]
	v_pk_fma_f32 v[136:137], v[26:27], v[128:129], v[136:137]
	v_pk_fma_f32 v[140:141], v[28:29], v[142:143], v[134:135]
	v_pk_fma_f32 v[134:135], v[30:31], v[130:131], v[138:139]
	s_waitcnt lgkmcnt(3)
	v_lshlrev_b32_e32 v138, 16, v248
	v_and_b32_e32 v139, 0xffff0000, v248
	v_lshlrev_b32_e32 v128, 16, v249
	v_and_b32_e32 v129, 0xffff0000, v249
	v_lshlrev_b32_e32 v142, 16, v250
	v_and_b32_e32 v143, 0xffff0000, v250
	v_lshlrev_b32_e32 v144, 16, v251
	v_and_b32_e32 v145, 0xffff0000, v251
	v_pk_fma_f32 v[130:131], v[34:35], v[128:129], v[136:137]
	v_pk_fma_f32 v[128:129], v[32:33], v[138:139], v[132:133]
	v_pk_fma_f32 v[134:135], v[38:39], v[144:145], v[134:135]
	v_pk_fma_f32 v[132:133], v[36:37], v[142:143], v[140:141]
	ds_write_b128 v228, v[128:131] offset:4480
	ds_write_b128 v228, v[132:135] offset:4496
	v_cvt_pk_bf16_f32 v128, v128, v129
	v_cvt_pk_bf16_f32 v129, v130, v131
	v_cvt_pk_bf16_f32 v130, v132, v133
	v_cvt_pk_bf16_f32 v131, v134, v135
	ds_write_b128 v229, v[128:131] offset:1152
	s_waitcnt lgkmcnt(0)
	s_mov_b32 s0, 0x37d00d01
	s_mov_b32 s1, 0x37d00d01
	s_mov_b32 s26, 0x3ab60b61
	s_mov_b32 s27, 0x3ab60b61
	s_mov_b32 s72, 0x3c088889
	s_mov_b32 s73, 0x3c088889
	ds_read_b128 v[128:131], v222
	ds_read_b128 v[240:243], v222 offset:64
	v_mov_b32_e32 v248, 1.0
	v_mov_b32_e32 v250, 0xbfb8aa3b
	v_add_u32_e32 v249, 2304, v223
	s_waitcnt lgkmcnt(0)
	v_mfma_f32_16x16x32_bf16 v[144:147], v[128:131], v[40:43], 0
	v_mfma_f32_16x16x32_bf16 v[148:151], v[128:131], v[72:75], 0
	v_mfma_f32_16x16x32_bf16 v[144:147], v[240:243], v[44:47], v[144:147]
	v_mfma_f32_16x16x32_bf16 v[148:151], v[240:243], v[76:79], v[148:151]
	s_nop 7
	s_nop 7
	s_nop 7
	ds_read2_b32 v[246:247], v249 offset0:0 offset1:68
	v_add_f32_e64 v132, v144, v173
	v_add_f32_e64 v133, v145, v173
	v_add_f32_e64 v140, v148, v175
	v_add_f32_e64 v141, v149, v175
	v_pk_mul_f32 v[132:133], v[132:133], v[250:251] op_sel_hi:[1,0]
	v_pk_mul_f32 v[140:141], v[140:141], v[250:251] op_sel_hi:[1,0]
	v_exp_f32_e32 v132, v132
	v_exp_f32_e32 v133, v133
	v_exp_f32_e32 v140, v140
	v_exp_f32_e32 v141, v141
	v_pk_add_f32 v[132:133], v[132:133], v[248:249] op_sel_hi:[1,0]
	v_pk_add_f32 v[140:141], v[140:141], v[248:249] op_sel_hi:[1,0]
	v_rcp_f32_e32 v132, v132
	v_rcp_f32_e32 v133, v133
	v_rcp_f32_e32 v140, v140
	v_rcp_f32_e32 v141, v141
	v_pk_mul_f32 v[142:143], v[132:133], v[236:237] op_sel_hi:[1,0]
	v_mul_f32_e32 v192, 0x3fb8aa3b, v142
	v_mul_f32_e32 v193, 0x3fb8aa3b, v143
	v_pk_add_f32 v[142:143], v[142:143], v[142:143]
	v_exp_f32_e32 v192, v192
	v_exp_f32_e32 v193, v193
	v_pk_fma_f32 v[244:245], v[142:143], s[0:1], v[198:199] op_sel_hi:[1,1,0]
	v_pk_fma_f32 v[244:245], v[142:143], v[244:245], s[26:27]
	v_pk_fma_f32 v[244:245], v[142:143], v[244:245], s[72:73]
	v_fmaak_f32 v244, v142, v244, 0x3d2aaaab
	v_fmaak_f32 v245, v143, v245, 0x3d2aaaab
	v_fmaak_f32 v244, v142, v244, 0x3e2aaaab
	v_fmaak_f32 v245, v143, v245, 0x3e2aaaab
	v_fma_f32 v244, v142, v244, 0.5
	v_fma_f32 v245, v143, v245, 0.5
	v_pk_fma_f32 v[244:245], v[142:143], v[244:245], v[248:249] op_sel_hi:[1,1,0]
	v_pk_mul_f32 v[244:245], v[142:143], v[244:245] neg_lo:[0,1] neg_hi:[0,1]
	v_max_f32_e32 v244, 0, v244
	v_max_f32_e32 v245, 0, v245
	v_sqrt_f32_e32 v244, v244
	v_sqrt_f32_e32 v245, v245
	ds_write_b32 v223, v192 offset:6656
	ds_write_b32 v223, v193 offset:6928
	v_pk_mul_f32 v[244:245], v[140:141], v[244:245]
	s_waitcnt lgkmcnt(2)
	v_pk_mul_f32 v[244:245], v[246:247], v[244:245]
	ds_write2_b32 v249, v244, v245 offset0:0 offset1:68
	ds_read2_b32 v[246:247], v249 offset0:136 offset1:204
	v_add_f32_e64 v132, v146, v173
	v_add_f32_e64 v133, v147, v173
	v_add_f32_e64 v140, v150, v175
	v_add_f32_e64 v141, v151, v175
	v_mfma_f32_16x16x32_bf16 v[144:147], v[128:131], v[48:51], 0
	v_mfma_f32_16x16x32_bf16 v[148:151], v[128:131], v[80:83], 0
	v_mfma_f32_16x16x32_bf16 v[144:147], v[240:243], v[52:55], v[144:147]
	v_mfma_f32_16x16x32_bf16 v[148:151], v[240:243], v[84:87], v[148:151]
	v_pk_mul_f32 v[132:133], v[132:133], v[250:251] op_sel_hi:[1,0]
	v_pk_mul_f32 v[140:141], v[140:141], v[250:251] op_sel_hi:[1,0]
	v_exp_f32_e32 v132, v132
	v_exp_f32_e32 v133, v133
	v_exp_f32_e32 v140, v140
	v_exp_f32_e32 v141, v141
	v_pk_add_f32 v[132:133], v[132:133], v[248:249] op_sel_hi:[1,0]
	v_pk_add_f32 v[140:141], v[140:141], v[248:249] op_sel_hi:[1,0]
	v_rcp_f32_e32 v132, v132
	v_rcp_f32_e32 v133, v133
	v_rcp_f32_e32 v140, v140
	v_rcp_f32_e32 v141, v141
	v_pk_mul_f32 v[142:143], v[132:133], v[236:237] op_sel_hi:[1,0]
	v_mul_f32_e32 v192, 0x3fb8aa3b, v142
	v_mul_f32_e32 v193, 0x3fb8aa3b, v143
	v_pk_add_f32 v[142:143], v[142:143], v[142:143]
	v_exp_f32_e32 v192, v192
	v_exp_f32_e32 v193, v193
	v_pk_fma_f32 v[244:245], v[142:143], s[0:1], v[198:199] op_sel_hi:[1,1,0]
	v_pk_fma_f32 v[244:245], v[142:143], v[244:245], s[26:27]
	v_pk_fma_f32 v[244:245], v[142:143], v[244:245], s[72:73]
	v_fmaak_f32 v244, v142, v244, 0x3d2aaaab
	v_fmaak_f32 v245, v143, v245, 0x3d2aaaab
	v_fmaak_f32 v244, v142, v244, 0x3e2aaaab
	v_fmaak_f32 v245, v143, v245, 0x3e2aaaab
	v_fma_f32 v244, v142, v244, 0.5
	v_fma_f32 v245, v143, v245, 0.5
	v_pk_fma_f32 v[244:245], v[142:143], v[244:245], v[248:249] op_sel_hi:[1,1,0]
	v_pk_mul_f32 v[244:245], v[142:143], v[244:245] neg_lo:[0,1] neg_hi:[0,1]
	v_max_f32_e32 v244, 0, v244
	v_max_f32_e32 v245, 0, v245
	v_sqrt_f32_e32 v244, v244
	v_sqrt_f32_e32 v245, v245
	ds_write_b32 v223, v192 offset:7200
	ds_write_b32 v223, v193 offset:7472
	v_pk_mul_f32 v[244:245], v[140:141], v[244:245]
	s_waitcnt lgkmcnt(2)
	v_pk_mul_f32 v[244:245], v[246:247], v[244:245]
	ds_write2_b32 v249, v244, v245 offset0:136 offset1:204
	ds_read2_b32 v[246:247], v249 offset0:16 offset1:84
	v_pk_add_f32 v[132:133], v[144:145], v[230:231] op_sel_hi:[1,0]
	v_add_f32_e64 v140, v148, v231
	v_add_f32_e64 v141, v149, v231
	v_pk_mul_f32 v[132:133], v[132:133], v[250:251] op_sel_hi:[1,0]
	v_pk_mul_f32 v[140:141], v[140:141], v[250:251] op_sel_hi:[1,0]
	v_exp_f32_e32 v132, v132
	v_exp_f32_e32 v133, v133
	v_exp_f32_e32 v140, v140
	v_exp_f32_e32 v141, v141
	v_pk_add_f32 v[132:133], v[132:133], v[248:249] op_sel_hi:[1,0]
	v_pk_add_f32 v[140:141], v[140:141], v[248:249] op_sel_hi:[1,0]
	v_rcp_f32_e32 v132, v132
	v_rcp_f32_e32 v133, v133
	v_rcp_f32_e32 v140, v140
	v_rcp_f32_e32 v141, v141
	v_mul_f32_e64 v142, v132, v237
	v_mul_f32_e64 v143, v133, v237
	v_mul_f32_e32 v192, 0x3fb8aa3b, v142
	v_mul_f32_e32 v193, 0x3fb8aa3b, v143
	v_pk_add_f32 v[142:143], v[142:143], v[142:143]
	v_exp_f32_e32 v192, v192
	v_exp_f32_e32 v193, v193
	v_pk_fma_f32 v[244:245], v[142:143], s[0:1], v[198:199] op_sel_hi:[1,1,0]
	v_pk_fma_f32 v[244:245], v[142:143], v[244:245], s[26:27]
	v_pk_fma_f32 v[244:245], v[142:143], v[244:245], s[72:73]
	v_fmaak_f32 v244, v142, v244, 0x3d2aaaab
	v_fmaak_f32 v245, v143, v245, 0x3d2aaaab
	v_fmaak_f32 v244, v142, v244, 0x3e2aaaab
	v_fmaak_f32 v245, v143, v245, 0x3e2aaaab
	v_fma_f32 v244, v142, v244, 0.5
	v_fma_f32 v245, v143, v245, 0.5
	v_pk_fma_f32 v[244:245], v[142:143], v[244:245], v[248:249] op_sel_hi:[1,1,0]
	v_pk_mul_f32 v[244:245], v[142:143], v[244:245] neg_lo:[0,1] neg_hi:[0,1]
	v_max_f32_e32 v244, 0, v244
	v_max_f32_e32 v245, 0, v245
	v_sqrt_f32_e32 v244, v244
	v_sqrt_f32_e32 v245, v245
	ds_write_b32 v223, v192 offset:6720
	ds_write_b32 v223, v193 offset:6992
	v_pk_mul_f32 v[244:245], v[140:141], v[244:245]
	s_waitcnt lgkmcnt(2)
	v_pk_mul_f32 v[244:245], v[246:247], v[244:245]
	ds_write2_b32 v249, v244, v245 offset0:16 offset1:84
	ds_read2_b32 v[246:247], v249 offset0:152 offset1:220
	v_pk_add_f32 v[132:133], v[146:147], v[230:231] op_sel_hi:[1,0]
	v_add_f32_e64 v140, v150, v231
	v_add_f32_e64 v141, v151, v231
	v_mfma_f32_16x16x32_bf16 v[144:147], v[128:131], v[56:59], 0
	v_mfma_f32_16x16x32_bf16 v[148:151], v[128:131], v[88:91], 0
	v_mfma_f32_16x16x32_bf16 v[144:147], v[240:243], v[60:63], v[144:147]
	v_mfma_f32_16x16x32_bf16 v[148:151], v[240:243], v[92:95], v[148:151]
	v_pk_mul_f32 v[132:133], v[132:133], v[250:251] op_sel_hi:[1,0]
	v_pk_mul_f32 v[140:141], v[140:141], v[250:251] op_sel_hi:[1,0]
	v_exp_f32_e32 v132, v132
	v_exp_f32_e32 v133, v133
	v_exp_f32_e32 v140, v140
	v_exp_f32_e32 v141, v141
	v_pk_add_f32 v[132:133], v[132:133], v[248:249] op_sel_hi:[1,0]
	v_pk_add_f32 v[140:141], v[140:141], v[248:249] op_sel_hi:[1,0]
	v_rcp_f32_e32 v132, v132
	v_rcp_f32_e32 v133, v133
	v_rcp_f32_e32 v140, v140
	v_rcp_f32_e32 v141, v141
	v_mul_f32_e64 v142, v132, v237
	v_mul_f32_e64 v143, v133, v237
	v_mul_f32_e32 v192, 0x3fb8aa3b, v142
	v_mul_f32_e32 v193, 0x3fb8aa3b, v143
	v_pk_add_f32 v[142:143], v[142:143], v[142:143]
	v_exp_f32_e32 v192, v192
	v_exp_f32_e32 v193, v193
	v_pk_fma_f32 v[244:245], v[142:143], s[0:1], v[198:199] op_sel_hi:[1,1,0]
	v_pk_fma_f32 v[244:245], v[142:143], v[244:245], s[26:27]
	v_pk_fma_f32 v[244:245], v[142:143], v[244:245], s[72:73]
	v_fmaak_f32 v244, v142, v244, 0x3d2aaaab
	v_fmaak_f32 v245, v143, v245, 0x3d2aaaab
	v_fmaak_f32 v244, v142, v244, 0x3e2aaaab
	v_fmaak_f32 v245, v143, v245, 0x3e2aaaab
	v_fma_f32 v244, v142, v244, 0.5
	v_fma_f32 v245, v143, v245, 0.5
	v_pk_fma_f32 v[244:245], v[142:143], v[244:245], v[248:249] op_sel_hi:[1,1,0]
	v_pk_mul_f32 v[244:245], v[142:143], v[244:245] neg_lo:[0,1] neg_hi:[0,1]
	v_max_f32_e32 v244, 0, v244
	v_max_f32_e32 v245, 0, v245
	v_sqrt_f32_e32 v244, v244
	v_sqrt_f32_e32 v245, v245
	ds_write_b32 v223, v192 offset:7264
	ds_write_b32 v223, v193 offset:7536
	v_pk_mul_f32 v[244:245], v[140:141], v[244:245]
	s_waitcnt lgkmcnt(2)
	v_pk_mul_f32 v[244:245], v[246:247], v[244:245]
	ds_write2_b32 v249, v244, v245 offset0:152 offset1:220
	ds_read2_b32 v[246:247], v249 offset0:32 offset1:100
	v_pk_add_f32 v[132:133], v[144:145], v[232:233] op_sel_hi:[1,0]
	v_add_f32_e64 v140, v148, v233
	v_add_f32_e64 v141, v149, v233
	v_pk_mul_f32 v[132:133], v[132:133], v[250:251] op_sel_hi:[1,0]
	v_pk_mul_f32 v[140:141], v[140:141], v[250:251] op_sel_hi:[1,0]
	v_exp_f32_e32 v132, v132
	v_exp_f32_e32 v133, v133
	v_exp_f32_e32 v140, v140
	v_exp_f32_e32 v141, v141
	v_pk_add_f32 v[132:133], v[132:133], v[248:249] op_sel_hi:[1,0]
	v_pk_add_f32 v[140:141], v[140:141], v[248:249] op_sel_hi:[1,0]
	v_rcp_f32_e32 v132, v132
	v_rcp_f32_e32 v133, v133
	v_rcp_f32_e32 v140, v140
	v_rcp_f32_e32 v141, v141
	v_pk_mul_f32 v[142:143], v[132:133], v[238:239] op_sel_hi:[1,0]
	v_mul_f32_e32 v192, 0x3fb8aa3b, v142
	v_mul_f32_e32 v193, 0x3fb8aa3b, v143
	v_pk_add_f32 v[142:143], v[142:143], v[142:143]
	v_exp_f32_e32 v192, v192
	v_exp_f32_e32 v193, v193
	v_pk_fma_f32 v[244:245], v[142:143], s[0:1], v[198:199] op_sel_hi:[1,1,0]
	v_pk_fma_f32 v[244:245], v[142:143], v[244:245], s[26:27]
	v_pk_fma_f32 v[244:245], v[142:143], v[244:245], s[72:73]
	v_fmaak_f32 v244, v142, v244, 0x3d2aaaab
	v_fmaak_f32 v245, v143, v245, 0x3d2aaaab
	v_fmaak_f32 v244, v142, v244, 0x3e2aaaab
	v_fmaak_f32 v245, v143, v245, 0x3e2aaaab
	v_fma_f32 v244, v142, v244, 0.5
	v_fma_f32 v245, v143, v245, 0.5
	v_pk_fma_f32 v[244:245], v[142:143], v[244:245], v[248:249] op_sel_hi:[1,1,0]
	v_pk_mul_f32 v[244:245], v[142:143], v[244:245] neg_lo:[0,1] neg_hi:[0,1]
	v_max_f32_e32 v244, 0, v244
	v_max_f32_e32 v245, 0, v245
	v_sqrt_f32_e32 v244, v244
	v_sqrt_f32_e32 v245, v245
	ds_write_b32 v223, v192 offset:6784
	ds_write_b32 v223, v193 offset:7056
	v_pk_mul_f32 v[244:245], v[140:141], v[244:245]
	s_waitcnt lgkmcnt(2)
	v_pk_mul_f32 v[244:245], v[246:247], v[244:245]
	ds_write2_b32 v249, v244, v245 offset0:32 offset1:100
	ds_read2_b32 v[246:247], v249 offset0:168 offset1:236
	v_pk_add_f32 v[132:133], v[146:147], v[232:233] op_sel_hi:[1,0]
	v_add_f32_e64 v140, v150, v233
	v_add_f32_e64 v141, v151, v233
	v_mfma_f32_16x16x32_bf16 v[144:147], v[128:131], v[64:67], 0
	v_mfma_f32_16x16x32_bf16 v[148:151], v[128:131], v[100:103], 0
	v_mfma_f32_16x16x32_bf16 v[144:147], v[240:243], v[68:71], v[144:147]
	v_mfma_f32_16x16x32_bf16 v[148:151], v[240:243], v[104:107], v[148:151]
	v_pk_mul_f32 v[132:133], v[132:133], v[250:251] op_sel_hi:[1,0]
	v_pk_mul_f32 v[140:141], v[140:141], v[250:251] op_sel_hi:[1,0]
	v_exp_f32_e32 v132, v132
	v_exp_f32_e32 v133, v133
	v_exp_f32_e32 v140, v140
	v_exp_f32_e32 v141, v141
	v_pk_add_f32 v[132:133], v[132:133], v[248:249] op_sel_hi:[1,0]
	v_pk_add_f32 v[140:141], v[140:141], v[248:249] op_sel_hi:[1,0]
	v_rcp_f32_e32 v132, v132
	v_rcp_f32_e32 v133, v133
	v_rcp_f32_e32 v140, v140
	v_rcp_f32_e32 v141, v141
	v_pk_mul_f32 v[142:143], v[132:133], v[238:239] op_sel_hi:[1,0]
	v_mul_f32_e32 v192, 0x3fb8aa3b, v142
	v_mul_f32_e32 v193, 0x3fb8aa3b, v143
	v_pk_add_f32 v[142:143], v[142:143], v[142:143]
	v_exp_f32_e32 v192, v192
	v_exp_f32_e32 v193, v193
	v_pk_fma_f32 v[244:245], v[142:143], s[0:1], v[198:199] op_sel_hi:[1,1,0]
	v_pk_fma_f32 v[244:245], v[142:143], v[244:245], s[26:27]
	v_pk_fma_f32 v[244:245], v[142:143], v[244:245], s[72:73]
	v_fmaak_f32 v244, v142, v244, 0x3d2aaaab
	v_fmaak_f32 v245, v143, v245, 0x3d2aaaab
	v_fmaak_f32 v244, v142, v244, 0x3e2aaaab
	v_fmaak_f32 v245, v143, v245, 0x3e2aaaab
	v_fma_f32 v244, v142, v244, 0.5
	v_fma_f32 v245, v143, v245, 0.5
	v_pk_fma_f32 v[244:245], v[142:143], v[244:245], v[248:249] op_sel_hi:[1,1,0]
	v_pk_mul_f32 v[244:245], v[142:143], v[244:245] neg_lo:[0,1] neg_hi:[0,1]
	v_max_f32_e32 v244, 0, v244
	v_max_f32_e32 v245, 0, v245
	v_sqrt_f32_e32 v244, v244
	v_sqrt_f32_e32 v245, v245
	ds_write_b32 v223, v192 offset:7328
	ds_write_b32 v223, v193 offset:7600
	v_pk_mul_f32 v[244:245], v[140:141], v[244:245]
	s_waitcnt lgkmcnt(2)
	v_pk_mul_f32 v[244:245], v[246:247], v[244:245]
	ds_write2_b32 v249, v244, v245 offset0:168 offset1:236
	ds_read2_b32 v[246:247], v249 offset0:48 offset1:116
	v_add_f32_e64 v132, v144, v235
	v_add_f32_e64 v133, v145, v235
	v_pk_add_f32 v[140:141], v[148:149], v[234:235] op_sel_hi:[1,0]
	v_pk_mul_f32 v[132:133], v[132:133], v[250:251] op_sel_hi:[1,0]
	v_pk_mul_f32 v[140:141], v[140:141], v[250:251] op_sel_hi:[1,0]
	v_exp_f32_e32 v132, v132
	v_exp_f32_e32 v133, v133
	v_exp_f32_e32 v140, v140
	v_exp_f32_e32 v141, v141
	v_pk_add_f32 v[132:133], v[132:133], v[248:249] op_sel_hi:[1,0]
	v_pk_add_f32 v[140:141], v[140:141], v[248:249] op_sel_hi:[1,0]
	v_rcp_f32_e32 v132, v132
	v_rcp_f32_e32 v133, v133
	v_rcp_f32_e32 v140, v140
	v_rcp_f32_e32 v141, v141
	v_mul_f32_e64 v142, v132, v239
	v_mul_f32_e64 v143, v133, v239
	v_mul_f32_e32 v192, 0x3fb8aa3b, v142
	v_mul_f32_e32 v193, 0x3fb8aa3b, v143
	v_pk_add_f32 v[142:143], v[142:143], v[142:143]
	v_exp_f32_e32 v192, v192
	v_exp_f32_e32 v193, v193
	v_pk_fma_f32 v[244:245], v[142:143], s[0:1], v[198:199] op_sel_hi:[1,1,0]
	v_pk_fma_f32 v[244:245], v[142:143], v[244:245], s[26:27]
	v_pk_fma_f32 v[244:245], v[142:143], v[244:245], s[72:73]
	v_fmaak_f32 v244, v142, v244, 0x3d2aaaab
	v_fmaak_f32 v245, v143, v245, 0x3d2aaaab
	v_fmaak_f32 v244, v142, v244, 0x3e2aaaab
	v_fmaak_f32 v245, v143, v245, 0x3e2aaaab
	v_fma_f32 v244, v142, v244, 0.5
	v_fma_f32 v245, v143, v245, 0.5
	v_pk_fma_f32 v[244:245], v[142:143], v[244:245], v[248:249] op_sel_hi:[1,1,0]
	v_pk_mul_f32 v[244:245], v[142:143], v[244:245] neg_lo:[0,1] neg_hi:[0,1]
	v_max_f32_e32 v244, 0, v244
	v_max_f32_e32 v245, 0, v245
	v_sqrt_f32_e32 v244, v244
	v_sqrt_f32_e32 v245, v245
	ds_write_b32 v223, v192 offset:6848
	ds_write_b32 v223, v193 offset:7120
	v_pk_mul_f32 v[244:245], v[140:141], v[244:245]
	s_waitcnt lgkmcnt(2)
	v_pk_mul_f32 v[244:245], v[246:247], v[244:245]
	ds_write2_b32 v249, v244, v245 offset0:48 offset1:116
	ds_read2_b32 v[246:247], v249 offset0:184 offset1:252
	v_add_f32_e64 v132, v146, v235
	v_add_f32_e64 v133, v147, v235
	v_pk_add_f32 v[140:141], v[150:151], v[234:235] op_sel_hi:[1,0]
	v_pk_mul_f32 v[132:133], v[132:133], v[250:251] op_sel_hi:[1,0]
	v_pk_mul_f32 v[140:141], v[140:141], v[250:251] op_sel_hi:[1,0]
	v_exp_f32_e32 v132, v132
	v_exp_f32_e32 v133, v133
	v_exp_f32_e32 v140, v140
	v_exp_f32_e32 v141, v141
	v_pk_add_f32 v[132:133], v[132:133], v[248:249] op_sel_hi:[1,0]
	v_pk_add_f32 v[140:141], v[140:141], v[248:249] op_sel_hi:[1,0]
	v_rcp_f32_e32 v132, v132
	v_rcp_f32_e32 v133, v133
	v_rcp_f32_e32 v140, v140
	v_rcp_f32_e32 v141, v141
	v_mul_f32_e64 v142, v132, v239
	v_mul_f32_e64 v143, v133, v239
	v_mul_f32_e32 v192, 0x3fb8aa3b, v142
	v_mul_f32_e32 v193, 0x3fb8aa3b, v143
	v_pk_add_f32 v[142:143], v[142:143], v[142:143]
	v_exp_f32_e32 v192, v192
	v_exp_f32_e32 v193, v193
	v_pk_fma_f32 v[244:245], v[142:143], s[0:1], v[198:199] op_sel_hi:[1,1,0]
	v_pk_fma_f32 v[244:245], v[142:143], v[244:245], s[26:27]
	v_pk_fma_f32 v[244:245], v[142:143], v[244:245], s[72:73]
	v_fmaak_f32 v244, v142, v244, 0x3d2aaaab
	v_fmaak_f32 v245, v143, v245, 0x3d2aaaab
	v_fmaak_f32 v244, v142, v244, 0x3e2aaaab
	v_fmaak_f32 v245, v143, v245, 0x3e2aaaab
	v_fma_f32 v244, v142, v244, 0.5
	v_fma_f32 v245, v143, v245, 0.5
	v_pk_fma_f32 v[244:245], v[142:143], v[244:245], v[248:249] op_sel_hi:[1,1,0]
	v_pk_mul_f32 v[244:245], v[142:143], v[244:245] neg_lo:[0,1] neg_hi:[0,1]
	v_max_f32_e32 v244, 0, v244
	v_max_f32_e32 v245, 0, v245
	v_sqrt_f32_e32 v244, v244
	v_sqrt_f32_e32 v245, v245
	ds_write_b32 v223, v192 offset:7392
	ds_write_b32 v223, v193 offset:7664
	v_pk_mul_f32 v[244:245], v[140:141], v[244:245]
	s_waitcnt lgkmcnt(2)
	v_pk_mul_f32 v[244:245], v[246:247], v[244:245]
	ds_write2_b32 v249, v244, v245 offset0:184 offset1:252
	s_waitcnt vmcnt(1)
	v_lshlrev_b32_e32 v139, 16, v127
	v_and_b32_e32 v127, 0xffff0000, v127
	v_lshlrev_b32_e32 v137, 16, v125
	v_and_b32_e32 v125, 0xffff0000, v125
	v_lshlrev_b32_e32 v138, 16, v126
	v_and_b32_e32 v126, 0xffff0000, v126
	v_add_u32_e32 v134, 0xa00, v227
	s_waitcnt lgkmcnt(0)
	v_add_u32_e32 v128, 0x1800, v227
	v_add_u32_e32 v132, 0x800, v227
	ds_read2_b32 v[128:129], v128 offset0:128 offset1:196
	ds_read2_b32 v[130:131], v132 offset0:64 offset1:132
	v_lshlrev_b32_e32 v136, 16, v124
	v_mul_f32_e32 v140, 0x3d372713, v136
	v_mul_f32_e32 v140, v140, v136
	v_and_b32_e32 v124, 0xffff0000, v124
	s_waitcnt lgkmcnt(0)
	v_fma_f32 v128, v177, v128, v130
	v_fmac_f32_e32 v131, v128, v129
	v_add_u32_e32 v130, 0x1c00, v227
	ds_write2_b32 v132, v128, v131 offset0:64 offset1:132
	ds_read2_b32 v[128:129], v130 offset0:8 offset1:76
	ds_read2_b32 v[132:133], v134 offset0:72 offset1:140
	s_waitcnt lgkmcnt(0)
	v_fma_f32 v128, v131, v128, v132
	v_fmac_f32_e32 v133, v128, v129
	v_add_u32_e32 v132, 0xc00, v227
	ds_write2_b32 v134, v128, v133 offset0:72 offset1:140
	ds_read2_b32 v[128:129], v130 offset0:144 offset1:212
	ds_read2_b32 v[130:131], v132 offset0:80 offset1:148
	v_add_u32_e32 v134, 0xe00, v227
	s_waitcnt lgkmcnt(0)
	v_fma_f32 v128, v133, v128, v130
	v_fmac_f32_e32 v131, v128, v129
	v_add_u32_e32 v130, 0x2000, v227
	ds_write2_b32 v132, v128, v131 offset0:80 offset1:148
	ds_read2_b32 v[128:129], v130 offset0:24 offset1:92
	ds_read2_b32 v[132:133], v134 offset0:88 offset1:156
	s_waitcnt lgkmcnt(0)
	v_fma_f32 v128, v131, v128, v132
	v_fmac_f32_e32 v133, v128, v129
	v_add_u32_e32 v132, 0x1000, v227
	ds_write2_b32 v134, v128, v133 offset0:88 offset1:156
	ds_read2_b32 v[128:129], v130 offset0:160 offset1:228
	ds_read2_b32 v[130:131], v132 offset0:96 offset1:164
	v_add_u32_e32 v134, 0x1200, v227
	s_waitcnt lgkmcnt(0)
	v_fma_f32 v128, v133, v128, v130
	v_fmac_f32_e32 v131, v128, v129
	v_add_u32_e32 v130, 0x2400, v227
	ds_write2_b32 v132, v128, v131 offset0:96 offset1:164
	ds_read2_b32 v[128:129], v130 offset0:40 offset1:108
	ds_read2_b32 v[132:133], v134 offset0:104 offset1:172
	s_waitcnt lgkmcnt(0)
	v_fma_f32 v128, v131, v128, v132
	v_fmac_f32_e32 v133, v128, v129
	v_add_u32_e32 v132, 0x1400, v227
	ds_write2_b32 v134, v128, v133 offset0:104 offset1:172
	ds_read2_b32 v[128:129], v130 offset0:176 offset1:244
	ds_read2_b32 v[130:131], v132 offset0:112 offset1:180
	s_waitcnt lgkmcnt(0)
	v_fma_f32 v128, v133, v128, v130
	v_fmac_f32_e32 v131, v128, v129
	ds_write2_b32 v132, v128, v131 offset0:112 offset1:180
	v_add_u32_e32 v128, 0x2800, v227
	v_add_u32_e32 v130, 0x1600, v227
	ds_read2_b32 v[128:129], v128 offset0:56 offset1:124
	ds_read2_b32 v[176:177], v130 offset0:120 offset1:188
	s_waitcnt lgkmcnt(0)
	v_fma_f32 v128, v131, v128, v176
	v_fmac_f32_e32 v177, v128, v129
	ds_write2_b32 v130, v128, v177 offset0:120 offset1:188
	s_waitcnt lgkmcnt(0)
	ds_read_b128 v[128:131], v228 offset:2304
	ds_read_b128 v[132:135], v228 offset:2320
	s_waitcnt lgkmcnt(1)
	v_mul_f32_e32 v128, v128, v136
	v_fmac_f32_e32 v136, v140, v136
	v_mul_f32_e32 v136, 0x3fcc422a, v136
	v_mul_f32_e32 v136, 0xbfb8aa3b, v136
	v_exp_f32_e32 v136, v136
	v_mul_f32_e32 v129, v129, v124
	v_add_f32_e32 v136, 1.0, v136
	v_rcp_f32_e32 v136, v136
	s_nop 0
	v_mul_f32_e32 v128, v136, v128
	v_mul_f32_e32 v136, 0x3d372713, v124
	v_mul_f32_e32 v136, v136, v124
	v_fmac_f32_e32 v124, v136, v124
	v_mul_f32_e32 v124, 0x3fcc422a, v124
	v_mul_f32_e32 v124, 0xbfb8aa3b, v124
	v_exp_f32_e32 v124, v124
	s_nop 0
	v_add_f32_e32 v124, 1.0, v124
	v_rcp_f32_e32 v124, v124
	s_nop 0
	v_mul_f32_e32 v124, v124, v129
	v_mul_f32_e32 v129, v130, v137
	v_mul_f32_e32 v130, 0x3d372713, v137
	v_mul_f32_e32 v130, v130, v137
	v_fmac_f32_e32 v137, v130, v137
	v_mul_f32_e32 v130, 0x3fcc422a, v137
	v_mul_f32_e32 v130, 0xbfb8aa3b, v130
	v_exp_f32_e32 v130, v130
	v_cvt_pk_bf16_f32 v124, v128, v124
	s_nop 0
	v_add_f32_e32 v130, 1.0, v130
	v_rcp_f32_e32 v130, v130
	s_nop 0
	v_mul_f32_e32 v129, v130, v129
	v_mul_f32_e32 v130, v131, v125
	v_mul_f32_e32 v131, 0x3d372713, v125
	v_mul_f32_e32 v131, v131, v125
	v_fmac_f32_e32 v125, v131, v125
	v_mul_f32_e32 v125, 0x3fcc422a, v125
	v_mul_f32_e32 v125, 0xbfb8aa3b, v125
	v_exp_f32_e32 v125, v125
	v_mul_f32_e32 v131, 0x3d372713, v138
	v_mul_f32_e32 v131, v131, v138
	v_add_f32_e32 v125, 1.0, v125
	v_rcp_f32_e32 v125, v125
	s_nop 0
	v_mul_f32_e32 v125, v125, v130
	s_waitcnt lgkmcnt(0)
	v_mul_f32_e32 v130, v132, v138
	v_fmac_f32_e32 v138, v131, v138
	v_mul_f32_e32 v131, 0x3fcc422a, v138
	v_mul_f32_e32 v131, 0xbfb8aa3b, v131
	v_exp_f32_e32 v131, v131
	v_mul_f32_e32 v132, 0x3d372713, v126
	v_mul_f32_e32 v132, v132, v126
	v_cvt_pk_bf16_f32 v125, v129, v125
	v_add_f32_e32 v131, 1.0, v131
	v_rcp_f32_e32 v131, v131
	v_lshl_add_u64 v[128:129], v[188:189], 0, v[166:167]
	v_lshl_add_u64 v[188:189], v[188:189], 0, s[60:61]
	v_mul_f32_e32 v130, v131, v130
	v_mul_f32_e32 v131, v133, v126
	v_fmac_f32_e32 v126, v132, v126
	v_mul_f32_e32 v126, 0x3fcc422a, v126
	v_mul_f32_e32 v126, 0xbfb8aa3b, v126
	v_exp_f32_e32 v126, v126
	v_mul_f32_e32 v132, 0x3d372713, v139
	v_mul_f32_e32 v132, v132, v139
	v_mul_f32_e32 v133, 0x3d372713, v127
	v_add_f32_e32 v126, 1.0, v126
	v_rcp_f32_e32 v126, v126
	v_mul_f32_e32 v133, v133, v127
	v_mul_f32_e32 v126, v126, v131
	v_mul_f32_e32 v131, v134, v139
	v_fmac_f32_e32 v139, v132, v139
	v_mul_f32_e32 v132, 0x3fcc422a, v139
	v_mul_f32_e32 v132, 0xbfb8aa3b, v132
	v_exp_f32_e32 v132, v132
	v_cvt_pk_bf16_f32 v126, v130, v126
	s_waitcnt vmcnt(0)
	v_lshlrev_b32_e32 v134, 16, v122
	v_and_b32_e32 v122, 0xffff0000, v122
	v_add_f32_e32 v132, 1.0, v132
	v_rcp_f32_e32 v132, v132
	s_nop 0
	v_mul_f32_e32 v131, v132, v131
	v_mul_f32_e32 v132, v135, v127
	v_fmac_f32_e32 v127, v133, v127
	v_mul_f32_e32 v127, 0x3fcc422a, v127
	v_mul_f32_e32 v127, 0xbfb8aa3b, v127
	v_exp_f32_e32 v127, v127
	v_lshlrev_b32_e32 v133, 16, v121
	v_and_b32_e32 v121, 0xffff0000, v121
	v_lshlrev_b32_e32 v135, 16, v123
	v_add_f32_e32 v127, 1.0, v127
	v_rcp_f32_e32 v127, v127
	v_and_b32_e32 v123, 0xffff0000, v123
	v_mul_f32_e32 v127, v127, v132
	v_cvt_pk_bf16_f32 v127, v131, v127
	global_store_dwordx4 v[128:129], v[124:127], off
	ds_read_b128 v[124:127], v228 offset:4480
	ds_read_b128 v[128:131], v228 offset:4496
	v_lshlrev_b32_e32 v132, 16, v120
	v_mul_f32_e32 v136, 0x3d372713, v132
	v_mul_f32_e32 v136, v136, v132
	s_waitcnt lgkmcnt(1)
	v_mul_f32_e32 v124, v124, v132
	v_fmac_f32_e32 v132, v136, v132
	v_mul_f32_e32 v132, 0x3fcc422a, v132
	v_mul_f32_e32 v132, 0xbfb8aa3b, v132
	v_exp_f32_e32 v132, v132
	v_and_b32_e32 v120, 0xffff0000, v120
	v_mul_f32_e32 v125, v125, v120
	v_add_f32_e32 v132, 1.0, v132
	v_rcp_f32_e32 v132, v132
	s_nop 0
	v_mul_f32_e32 v124, v132, v124
	v_mul_f32_e32 v132, 0x3d372713, v120
	v_mul_f32_e32 v132, v132, v120
	v_fmac_f32_e32 v120, v132, v120
	v_mul_f32_e32 v120, 0x3fcc422a, v120
	v_mul_f32_e32 v120, 0xbfb8aa3b, v120
	v_exp_f32_e32 v120, v120
	s_nop 0
	v_add_f32_e32 v120, 1.0, v120
	v_rcp_f32_e32 v120, v120
	s_nop 0
	v_mul_f32_e32 v120, v120, v125
	v_mul_f32_e32 v125, v126, v133
	v_mul_f32_e32 v126, 0x3d372713, v133
	v_mul_f32_e32 v126, v126, v133
	v_fmac_f32_e32 v133, v126, v133
	v_mul_f32_e32 v126, 0x3fcc422a, v133
	v_mul_f32_e32 v126, 0xbfb8aa3b, v126
	v_exp_f32_e32 v126, v126
	v_cvt_pk_bf16_f32 v120, v124, v120
	s_nop 0
	v_add_f32_e32 v126, 1.0, v126
	v_rcp_f32_e32 v126, v126
	s_nop 0
	v_mul_f32_e32 v125, v126, v125
	v_mul_f32_e32 v126, v127, v121
	v_mul_f32_e32 v127, 0x3d372713, v121
	v_mul_f32_e32 v127, v127, v121
	v_fmac_f32_e32 v121, v127, v121
	v_mul_f32_e32 v121, 0x3fcc422a, v121
	v_mul_f32_e32 v121, 0xbfb8aa3b, v121
	v_exp_f32_e32 v121, v121
	v_mul_f32_e32 v127, 0x3d372713, v134
	v_mul_f32_e32 v127, v127, v134
	v_add_f32_e32 v121, 1.0, v121
	v_rcp_f32_e32 v121, v121
	s_nop 0
	v_mul_f32_e32 v121, v121, v126
	s_waitcnt lgkmcnt(0)
	v_mul_f32_e32 v126, v128, v134
	v_fmac_f32_e32 v134, v127, v134
	v_mul_f32_e32 v127, 0x3fcc422a, v134
	v_mul_f32_e32 v127, 0xbfb8aa3b, v127
	v_exp_f32_e32 v127, v127
	v_mul_f32_e32 v128, 0x3d372713, v122
	v_mul_f32_e32 v128, v128, v122
	v_cvt_pk_bf16_f32 v121, v125, v121
	v_add_f32_e32 v127, 1.0, v127
	v_rcp_f32_e32 v127, v127
	v_lshl_add_u64 v[124:125], v[178:179], 0, v[166:167]
	v_lshl_add_u64 v[178:179], v[178:179], 0, s[60:61]
	v_mul_f32_e32 v126, v127, v126
	v_mul_f32_e32 v127, v129, v122
	v_fmac_f32_e32 v122, v128, v122
	v_mul_f32_e32 v122, 0x3fcc422a, v122
	v_mul_f32_e32 v122, 0xbfb8aa3b, v122
	v_exp_f32_e32 v122, v122
	v_mul_f32_e32 v128, 0x3d372713, v135
	v_mul_f32_e32 v128, v128, v135
	v_mul_f32_e32 v129, 0x3d372713, v123
	v_add_f32_e32 v122, 1.0, v122
	v_rcp_f32_e32 v122, v122
	v_mul_f32_e32 v129, v129, v123
	v_mul_f32_e32 v122, v122, v127
	v_mul_f32_e32 v127, v130, v135
	v_fmac_f32_e32 v135, v128, v135
	v_mul_f32_e32 v128, 0x3fcc422a, v135
	v_mul_f32_e32 v128, 0xbfb8aa3b, v128
	v_exp_f32_e32 v128, v128
	v_cvt_pk_bf16_f32 v122, v126, v122
	s_nop 0
	v_add_f32_e32 v128, 1.0, v128
	v_rcp_f32_e32 v128, v128
	s_nop 0
	v_mul_f32_e32 v127, v128, v127
	v_mul_f32_e32 v128, v131, v123
	v_fmac_f32_e32 v123, v129, v123
	v_mul_f32_e32 v123, 0x3fcc422a, v123
	v_mul_f32_e32 v123, 0xbfb8aa3b, v123
	v_exp_f32_e32 v123, v123
	s_nop 0
	v_add_f32_e32 v123, 1.0, v123
	v_rcp_f32_e32 v123, v123
	s_nop 0
	v_mul_f32_e32 v123, v123, v128
	v_cvt_pk_bf16_f32 v123, v127, v123
	global_store_dwordx4 v[124:125], v[120:123], off
	s_waitcnt lgkmcnt(0)
	s_cbranch_scc0 .LBB0_249
